# attention K staging: LDS waits that only served the removed ds_bpermute round trips deleted, so a trip's math overlaps the previous trip's LDS stores
# baseline (speedup 1.0000x reference)
; #define LAS __attribute__((address_space(3)))
; __device__ __forceinline__ void attn_phase(LAS unsigned char* lds, const bf16* qkv, bf16* o, const float* qg, const float* kg, const float* sink, int G, int c) {
;     ...
;         v4u qraw[2][4];
; #pragma unroll
;         for (int h = 0; h < 2; ++h) { const bf16* qp = qkv + (size_t)rowof(b, qpos) * QKVN + (head0 + h) * 64 + hh * 8;
; #pragma unroll
;             for (int kk = 0; kk < 4; ++kk) qraw[h][kk] = *(const v4u*)(qp + kk * 16); }
;         __syncthreads();
; #pragma unroll
;         for (int i = 0; i < 7; ++i) {
;             const int part = tid & 7, o = tid >> 3;
;             int slot = -1;
;             if (i < 6) { const int Bc = (meta ? 0 : j - 1) + (i >> 1); if (Bc >= Blo && Bc <= Bhi && (first || Bc == j + 1) && !(meta && i >= 2)) slot = (Bc % 3) * 128 + 64 * (i & 1) + o; }
;             else if (first && o < 32) slot = 384 + o;
;             const v4u kw = kr[i], vw = vr[i];
;             float kf[8] = {bflo(kw.x), bfhi(kw.x), bflo(kw.y), bfhi(kw.y), bflo(kw.z), bfhi(kw.z), bflo(kw.w), bfhi(kw.w)};
;             float ss = 0.f;
; #pragma unroll
;             for (int e = 0; e < 8; ++e) ss += kf[e] * kf[e];
;             ss += __shfl_xor(ss, 1); ss += __shfl_xor(ss, 2); ss += __shfl_xor(ss, 4);
;             const float rs = __builtin_amdgcn_rsqf(ss * (1.0f / 64.0f) + pg8::RMS_EPS);
;             const f32x4 g0 = *(const f32x4*)(kg + part * 8), g1 = *(const f32x4*)(kg + part * 8 + 4);
;             v4u kp; kp.x = pk2(kf[0] * rs * g0.x, kf[1] * rs * g0.y); kp.y = pk2(kf[2] * rs * g0.z, kf[3] * rs * g0.w);
;             kp.z = pk2(kf[4] * rs * g1.x, kf[5] * rs * g1.y); kp.w = pk2(kf[6] * rs * g1.z, kf[7] * rs * g1.w);
;             if (slot >= 0) {
;                 *(LAS v4u*)(lds + K_OFF + slot * KSTR + part * 16) = kp;
;                 LAS unsigned char* vb = lds + V_OFF + (part * 8) * VSTR + slot * 2;
;                 *(LAS unsigned short*)(vb + 0 * VSTR) = (unsigned short)(vw.x & 0xffffu); *(LAS unsigned short*)(vb + 1 * VSTR) = (unsigned short)(vw.x >> 16);
;                 *(LAS unsigned short*)(vb + 2 * VSTR) = (unsigned short)(vw.y & 0xffffu); *(LAS unsigned short*)(vb + 3 * VSTR) = (unsigned short)(vw.y >> 16);
;                 *(LAS unsigned short*)(vb + 4 * VSTR) = (unsigned short)(vw.z & 0xffffu); *(LAS unsigned short*)(vb + 5 * VSTR) = (unsigned short)(vw.z >> 16);
.LBB0_576:
	s_or_b64 exec, exec, s[40:41]
	s_lshl_b32 s4, s84, 7
	s_or_b32 s30, s4, s70
	v_mov_b32_e32 v0, s59
	v_mov_b32_e32 v1, s60
	s_or_b32 s31, s30, 16
	v_cndmask_b32_e64 v0, v0, v1, s[24:25]
	v_add_u32_e32 v1, s31, v153
	v_cndmask_b32_e64 v220, v1, v155, s[24:25]
	v_lshlrev_b32_e32 v0, 1, v0
	v_lshl_add_u32 v92, s85, 2, v0
	v_mov_b32_e32 v0, s6
	v_mov_b32_e32 v1, s7
	v_cmp_gt_i32_e64 s[42:43], 16, v220
	v_or_b32_e32 v93, 1, v92
	s_movk_i32 s4, 0xc00
	v_cndmask_b32_e64 v0, v0, v1, s[42:43]
	v_add_u32_e32 v164, v0, v220
	v_mov_b64_e32 v[0:1], s[62:63]
	v_lshlrev_b32_e32 v166, 6, v92
	v_lshlrev_b32_e32 v162, 6, v93
	v_mad_i64_i32 v[0:1], s[6:7], v164, s4, v[0:1]
	v_ashrrev_i32_e32 v167, 31, v166
	v_ashrrev_i32_e32 v163, 31, v162
	v_lshl_add_u64 v[2:3], v[166:167], 1, v[0:1]
	v_lshlrev_b32_e32 v194, 1, v152
	v_lshl_add_u64 v[0:1], v[162:163], 1, v[0:1]
	v_lshl_add_u64 v[2:3], v[2:3], 0, v[194:195]
	v_lshl_add_u64 v[0:1], v[0:1], 0, v[194:195]
	global_load_dwordx4 v[36:39], v[2:3], off
	global_load_dwordx4 v[32:35], v[2:3], off offset:32
	global_load_dwordx4 v[28:31], v[2:3], off offset:64
	global_load_dwordx4 v[20:23], v[2:3], off offset:96
	global_load_dwordx4 v[12:15], v[0:1], off
	global_load_dwordx4 v[8:11], v[0:1], off offset:32
	global_load_dwordx4 v[4:7], v[0:1], off offset:64
	s_nop 0
	global_load_dwordx4 v[0:3], v[0:1], off offset:96
	v_cmp_ge_i32_e64 s[42:43], v96, v218
	v_cmp_le_i32_e64 s[44:45], v96, v219
	s_and_b64 s[6:7], s[42:43], s[44:45]
	s_and_b64 s[42:43], s[6:7], vcc
	v_mov_b32_e32 v98, -1
	v_mul_lo_u16_e32 v97, 0xab, v96
	s_barrier
	s_and_saveexec_b64 s[40:41], s[42:43]
	v_lshrrev_b16_e32 v88, 9, v97
	v_mul_lo_u16_e32 v88, 3, v88
	v_sub_u16_e32 v88, v96, v88
	v_and_b32_e32 v88, 0xff, v88
	v_lshl_add_u32 v98, v88, 7, v183
	s_or_b64 exec, exec, s[40:41]
	s_waitcnt vmcnt(9)
	v_and_b32_e32 v100, 0xffff0000, v84
	v_lshlrev_b32_e32 v99, 16, v84
	v_mul_f32_e32 v84, v100, v100
	v_lshlrev_b32_e32 v101, 16, v85
	v_fmac_f32_e32 v84, v99, v99
	v_and_b32_e32 v102, 0xffff0000, v85
	v_fmac_f32_e32 v84, v101, v101
	v_lshlrev_b32_e32 v103, 16, v86
	v_fmac_f32_e32 v84, v102, v102
	v_and_b32_e32 v104, 0xffff0000, v86
	v_fmac_f32_e32 v84, v103, v103
	v_lshlrev_b32_e32 v105, 16, v87
	v_fmac_f32_e32 v84, v104, v104
	v_and_b32_e32 v106, 0xffff0000, v87
	v_fmac_f32_e32 v84, v105, v105
	v_fmac_f32_e32 v84, v106, v106
	s_nop 1
	v_add_f32_dpp v84, v84, v84 quad_perm:[1,0,3,2] row_mask:0xf bank_mask:0xf
	v_cmp_lt_i32_e32 vcc, -1, v98
	s_nop 1
	v_add_f32_dpp v84, v84, v84 quad_perm:[2,3,0,1] row_mask:0xf bank_mask:0xf
	s_nop 1
	v_add_f32_dpp v84, v84, v84 row_half_mirror row_mask:0xf bank_mask:0xf
	v_fmamk_f32 v84, v84, 0x3c800000, v193
	v_rsq_f32_e32 v107, v84
	global_load_dwordx4 v[84:87], v[158:159], off offset:16
	global_load_dwordx4 v[88:91], v[158:159], off
	v_mul_f32_e32 v99, v107, v99
	s_waitcnt vmcnt(0)
	v_mul_f32_e32 v88, v88, v99
	v_mul_f32_e32 v99, v107, v100
	v_mul_f32_e32 v89, v89, v99
	v_cvt_pk_bf16_f32 v88, v88, v89
	v_mul_f32_e32 v89, v107, v101
	v_mul_f32_e32 v89, v90, v89
	v_mul_f32_e32 v90, v107, v102
	v_mul_f32_e32 v90, v91, v90
	v_cvt_pk_bf16_f32 v89, v89, v90
	v_mul_f32_e32 v90, v107, v103
	v_mul_f32_e32 v84, v84, v90
	v_mul_f32_e32 v90, v107, v104
	v_mul_f32_e32 v85, v85, v90
	v_cvt_pk_bf16_f32 v90, v84, v85
	v_mul_f32_e32 v84, v107, v105
	v_mul_f32_e32 v85, v107, v106
	v_mul_f32_e32 v84, v86, v84
	v_mul_f32_e32 v85, v87, v85
	v_cvt_pk_bf16_f32 v91, v84, v85
	s_and_saveexec_b64 s[40:41], vcc
	s_cbranch_execz .LBB0_580
	s_movk_i32 s4, 0x90
	v_mad_u64_u32 v[84:85], s[6:7], v98, s4, v[154:155]
	ds_write_b128 v84, v[88:91]
	v_lshl_add_u32 v84, v98, 1, v214
	v_add_u32_e32 v85, 0xea00, v84
	ds_write_b16 v84, v80 offset:59904
	ds_write_b16_d16_hi v84, v80 offset:60744
	ds_write_b16 v84, v81 offset:61584
	ds_write_b16_d16_hi v84, v81 offset:62424
	ds_write_b16 v84, v82 offset:63264
	ds_write_b16_d16_hi v84, v82 offset:64104
	ds_write_b16 v84, v83 offset:64944
	ds_write_b16_d16_hi v85, v83 offset:5880
.LBB0_580:
	s_or_b64 exec, exec, s[40:41]
	v_mov_b32_e32 v84, -1
	s_and_saveexec_b64 s[40:41], s[42:43]
	v_lshrrev_b16_e32 v80, 9, v97
	v_mul_lo_u16_e32 v80, 3, v80
	v_sub_u16_e32 v80, v96, v80
	v_and_b32_e32 v80, 0xff, v80
	v_lshl_add_u32 v84, v80, 7, v213
	s_or_b64 exec, exec, s[40:41]
	v_and_b32_e32 v86, 0xffff0000, v76
	v_lshlrev_b32_e32 v85, 16, v76
	v_mul_f32_e32 v76, v86, v86
	v_lshlrev_b32_e32 v87, 16, v77
	v_fmac_f32_e32 v76, v85, v85
	v_and_b32_e32 v88, 0xffff0000, v77
	v_fmac_f32_e32 v76, v87, v87
	v_lshlrev_b32_e32 v89, 16, v78
	v_fmac_f32_e32 v76, v88, v88
	v_and_b32_e32 v90, 0xffff0000, v78
	v_fmac_f32_e32 v76, v89, v89
	v_lshlrev_b32_e32 v91, 16, v79
	v_fmac_f32_e32 v76, v90, v90
	v_and_b32_e32 v96, 0xffff0000, v79
	v_fmac_f32_e32 v76, v91, v91
	v_fmac_f32_e32 v76, v96, v96
	s_nop 1
	v_add_f32_dpp v76, v76, v76 quad_perm:[1,0,3,2] row_mask:0xf bank_mask:0xf
	v_cmp_lt_i32_e32 vcc, -1, v84
	s_nop 1
	v_add_f32_dpp v76, v76, v76 quad_perm:[2,3,0,1] row_mask:0xf bank_mask:0xf
	s_nop 1
	v_add_f32_dpp v76, v76, v76 row_half_mirror row_mask:0xf bank_mask:0xf
	v_fmamk_f32 v76, v76, 0x3c800000, v193
	v_rsq_f32_e32 v97, v76
	global_load_dwordx4 v[76:79], v[158:159], off offset:16
	global_load_dwordx4 v[80:83], v[158:159], off
	v_mul_f32_e32 v85, v97, v85
	s_waitcnt vmcnt(0)
	v_mul_f32_e32 v80, v80, v85
	v_mul_f32_e32 v85, v97, v86
	v_mul_f32_e32 v81, v81, v85
	v_cvt_pk_bf16_f32 v80, v80, v81
	v_mul_f32_e32 v81, v97, v87
	v_mul_f32_e32 v81, v82, v81
	v_mul_f32_e32 v82, v97, v88
	v_mul_f32_e32 v82, v83, v82
	v_cvt_pk_bf16_f32 v81, v81, v82
	v_mul_f32_e32 v82, v97, v89
	v_mul_f32_e32 v76, v76, v82
	v_mul_f32_e32 v82, v97, v90
	v_mul_f32_e32 v77, v77, v82
	v_cvt_pk_bf16_f32 v82, v76, v77
	v_mul_f32_e32 v76, v97, v91
	v_mul_f32_e32 v77, v97, v96
	v_mul_f32_e32 v76, v78, v76
	v_mul_f32_e32 v77, v79, v77
	v_cvt_pk_bf16_f32 v83, v76, v77
	s_and_saveexec_b64 s[40:41], vcc
	s_cbranch_execz .LBB0_584
	s_movk_i32 s4, 0x90
	v_mad_u64_u32 v[76:77], s[6:7], v84, s4, v[154:155]
	ds_write_b128 v76, v[80:83]
	v_lshl_add_u32 v76, v84, 1, v214
	v_add_u32_e32 v77, 0xea00, v76
	ds_write_b16 v76, v68 offset:59904
	ds_write_b16_d16_hi v76, v68 offset:60744
	ds_write_b16 v76, v69 offset:61584
	ds_write_b16_d16_hi v76, v69 offset:62424
	ds_write_b16 v76, v70 offset:63264
	ds_write_b16_d16_hi v76, v70 offset:64104
	ds_write_b16 v76, v71 offset:64944
	ds_write_b16_d16_hi v77, v71 offset:5880
; #define LAS __attribute__((address_space(3)))
; __device__ __forceinline__ unsigned pk2(float lo, float hi) { return pg8::cvt_pk_bf16(lo, hi); }
; __device__ __forceinline__ void attn_phase(LAS unsigned char* lds, const bf16* qkv, bf16* o, const float* qg, const float* kg, const float* sink, int G, int c) {
;     ...
;         for (int i = 0; i < 7; ++i) {
;             const int part = tid & 7, o = tid >> 3;
;             int slot = -1;
;             if (i < 6) { const int Bc = (meta ? 0 : j - 1) + (i >> 1); if (Bc >= Blo && Bc <= Bhi && (first || Bc == j + 1) && !(meta && i >= 2)) slot = (Bc % 3) * 128 + 64 * (i & 1) + o; }
;             else if (first && o < 32) slot = 384 + o;
;             const v4u kw = kr[i], vw = vr[i];
;             float kf[8] = {bflo(kw.x), bfhi(kw.x), bflo(kw.y), bfhi(kw.y), bflo(kw.z), bfhi(kw.z), bflo(kw.w), bfhi(kw.w)};
;             float ss = 0.f;
; #pragma unroll
;             for (int e = 0; e < 8; ++e) ss += kf[e] * kf[e];
;             ss += __shfl_xor(ss, 1); ss += __shfl_xor(ss, 2); ss += __shfl_xor(ss, 4);
;             const float rs = __builtin_amdgcn_rsqf(ss * (1.0f / 64.0f) + pg8::RMS_EPS);
;             const f32x4 g0 = *(const f32x4*)(kg + part * 8), g1 = *(const f32x4*)(kg + part * 8 + 4);
;             v4u kp; kp.x = pk2(kf[0] * rs * g0.x, kf[1] * rs * g0.y); kp.y = pk2(kf[2] * rs * g0.z, kf[3] * rs * g0.w);
;             kp.z = pk2(kf[4] * rs * g1.x, kf[5] * rs * g1.y); kp.w = pk2(kf[6] * rs * g1.z, kf[7] * rs * g1.w);
;             if (slot >= 0) {
;                 *(LAS v4u*)(lds + K_OFF + slot * KSTR + part * 16) = kp;
;                 LAS unsigned char* vb = lds + V_OFF + (part * 8) * VSTR + slot * 2;
;                 *(LAS unsigned short*)(vb + 0 * VSTR) = (unsigned short)(vw.x & 0xffffu); *(LAS unsigned short*)(vb + 1 * VSTR) = (unsigned short)(vw.x >> 16);
;                 *(LAS unsigned short*)(vb + 2 * VSTR) = (unsigned short)(vw.y & 0xffffu); *(LAS unsigned short*)(vb + 3 * VSTR) = (unsigned short)(vw.y >> 16);
;                 *(LAS unsigned short*)(vb + 4 * VSTR) = (unsigned short)(vw.z & 0xffffu); *(LAS unsigned short*)(vb + 5 * VSTR) = (unsigned short)(vw.z >> 16);
;                 *(LAS unsigned short*)(vb + 6 * VSTR) = (unsigned short)(vw.w & 0xffffu); *(LAS unsigned short*)(vb + 7 * VSTR) = (unsigned short)(vw.w >> 16);
;             }
.LBB0_584:
	s_or_b64 exec, exec, s[40:41]
	s_xor_b64 s[42:43], s[46:47], -1
	v_mov_b32_e32 v77, -1
	v_mul_lo_u16_e32 v76, 0xab, v95
	s_and_saveexec_b64 s[40:41], s[42:43]
	v_lshrrev_b16_e32 v68, 9, v76
	v_mul_lo_u16_e32 v68, 3, v68
	v_sub_u16_e32 v68, v95, v68
	v_and_b32_e32 v68, 0xff, v68
	v_lshl_add_u32 v77, v68, 7, v183
	s_or_b64 exec, exec, s[40:41]
	v_and_b32_e32 v79, 0xffff0000, v72
	v_lshlrev_b32_e32 v78, 16, v72
	v_mul_f32_e32 v68, v79, v79
	v_lshlrev_b32_e32 v80, 16, v73
	v_fmac_f32_e32 v68, v78, v78
	v_and_b32_e32 v81, 0xffff0000, v73
	v_fmac_f32_e32 v68, v80, v80
	v_lshlrev_b32_e32 v82, 16, v74
	v_fmac_f32_e32 v68, v81, v81
	v_and_b32_e32 v83, 0xffff0000, v74
	v_fmac_f32_e32 v68, v82, v82
	v_lshlrev_b32_e32 v84, 16, v75
	v_fmac_f32_e32 v68, v83, v83
	v_and_b32_e32 v85, 0xffff0000, v75
	v_fmac_f32_e32 v68, v84, v84
	v_fmac_f32_e32 v68, v85, v85
	s_nop 1
	v_add_f32_dpp v68, v68, v68 quad_perm:[1,0,3,2] row_mask:0xf bank_mask:0xf
	v_cmp_lt_i32_e32 vcc, -1, v77
	s_nop 1
	v_add_f32_dpp v68, v68, v68 quad_perm:[2,3,0,1] row_mask:0xf bank_mask:0xf
	s_nop 1
	v_add_f32_dpp v68, v68, v68 row_half_mirror row_mask:0xf bank_mask:0xf
	v_fmamk_f32 v68, v68, 0x3c800000, v193
	v_rsq_f32_e32 v86, v68
	global_load_dwordx4 v[68:71], v[158:159], off offset:16
	global_load_dwordx4 v[72:75], v[158:159], off
	v_mul_f32_e32 v78, v86, v78
	s_waitcnt vmcnt(0)
	v_mul_f32_e32 v72, v72, v78
	v_mul_f32_e32 v78, v86, v79
	v_mul_f32_e32 v73, v73, v78
	v_cvt_pk_bf16_f32 v72, v72, v73
	v_mul_f32_e32 v73, v86, v80
	v_mul_f32_e32 v73, v74, v73
	v_mul_f32_e32 v74, v86, v81
	v_mul_f32_e32 v74, v75, v74
	v_cvt_pk_bf16_f32 v73, v73, v74
	v_mul_f32_e32 v74, v86, v82
	v_mul_f32_e32 v68, v68, v74
	v_mul_f32_e32 v74, v86, v83
	v_mul_f32_e32 v69, v69, v74
	v_cvt_pk_bf16_f32 v74, v68, v69
	v_mul_f32_e32 v68, v86, v84
	v_mul_f32_e32 v69, v86, v85
	v_mul_f32_e32 v68, v70, v68
	v_mul_f32_e32 v69, v71, v69
	v_cvt_pk_bf16_f32 v75, v68, v69
	s_and_saveexec_b64 s[40:41], vcc
	s_cbranch_execz .LBB0_588
	s_movk_i32 s4, 0x90
	v_mad_u64_u32 v[68:69], s[6:7], v77, s4, v[154:155]
	ds_write_b128 v68, v[72:75]
	v_lshl_add_u32 v68, v77, 1, v214
	v_add_u32_e32 v69, 0xea00, v68
	ds_write_b16 v68, v64 offset:59904
	ds_write_b16_d16_hi v68, v64 offset:60744
	ds_write_b16 v68, v65 offset:61584
	ds_write_b16_d16_hi v68, v65 offset:62424
	ds_write_b16 v68, v66 offset:63264
	ds_write_b16_d16_hi v68, v66 offset:64104
	ds_write_b16 v68, v67 offset:64944
	ds_write_b16_d16_hi v69, v67 offset:5880
.LBB0_588:
	s_or_b64 exec, exec, s[40:41]
	v_mov_b32_e32 v68, -1
	s_and_saveexec_b64 s[40:41], s[42:43]
	v_lshrrev_b16_e32 v64, 9, v76
	v_mul_lo_u16_e32 v64, 3, v64
	v_sub_u16_e32 v64, v95, v64
	v_and_b32_e32 v64, 0xff, v64
	v_lshl_add_u32 v68, v64, 7, v213
	s_or_b64 exec, exec, s[40:41]
	v_and_b32_e32 v70, 0xffff0000, v60
	v_lshlrev_b32_e32 v69, 16, v60
	v_mul_f32_e32 v60, v70, v70
	v_lshlrev_b32_e32 v71, 16, v61
	v_fmac_f32_e32 v60, v69, v69
	v_and_b32_e32 v72, 0xffff0000, v61
	v_fmac_f32_e32 v60, v71, v71
	v_lshlrev_b32_e32 v73, 16, v62
	v_fmac_f32_e32 v60, v72, v72
	v_and_b32_e32 v74, 0xffff0000, v62
	v_fmac_f32_e32 v60, v73, v73
	v_lshlrev_b32_e32 v75, 16, v63
	v_fmac_f32_e32 v60, v74, v74
	v_and_b32_e32 v76, 0xffff0000, v63
	v_fmac_f32_e32 v60, v75, v75
	v_fmac_f32_e32 v60, v76, v76
	s_nop 1
	v_add_f32_dpp v60, v60, v60 quad_perm:[1,0,3,2] row_mask:0xf bank_mask:0xf
	v_cmp_lt_i32_e32 vcc, -1, v68
	s_nop 1
	v_add_f32_dpp v60, v60, v60 quad_perm:[2,3,0,1] row_mask:0xf bank_mask:0xf
	s_nop 1
	v_add_f32_dpp v60, v60, v60 row_half_mirror row_mask:0xf bank_mask:0xf
	v_fmamk_f32 v60, v60, 0x3c800000, v193
	v_rsq_f32_e32 v77, v60
	global_load_dwordx4 v[60:63], v[158:159], off offset:16
	global_load_dwordx4 v[64:67], v[158:159], off
	v_mul_f32_e32 v69, v77, v69
	s_waitcnt vmcnt(0)
	v_mul_f32_e32 v64, v64, v69
	v_mul_f32_e32 v69, v77, v70
	v_mul_f32_e32 v65, v65, v69
	v_cvt_pk_bf16_f32 v64, v64, v65
	v_mul_f32_e32 v65, v77, v71
	v_mul_f32_e32 v65, v66, v65
	v_mul_f32_e32 v66, v77, v72
	v_mul_f32_e32 v66, v67, v66
	v_cvt_pk_bf16_f32 v65, v65, v66
	v_mul_f32_e32 v66, v77, v73
	v_mul_f32_e32 v60, v60, v66
	v_mul_f32_e32 v66, v77, v74
	v_mul_f32_e32 v61, v61, v66
	v_cvt_pk_bf16_f32 v66, v60, v61
	v_mul_f32_e32 v60, v77, v75
	v_mul_f32_e32 v61, v77, v76
	v_mul_f32_e32 v60, v62, v60
	v_mul_f32_e32 v61, v63, v61
	v_cvt_pk_bf16_f32 v67, v60, v61
	s_and_saveexec_b64 s[40:41], vcc
	s_cbranch_execz .LBB0_592
	s_movk_i32 s4, 0x90
	v_mad_u64_u32 v[60:61], s[6:7], v68, s4, v[154:155]
	ds_write_b128 v60, v[64:67]
	v_lshl_add_u32 v60, v68, 1, v214
	v_add_u32_e32 v61, 0xea00, v60
	ds_write_b16 v60, v52 offset:59904
	ds_write_b16_d16_hi v60, v52 offset:60744
	ds_write_b16 v60, v53 offset:61584
	ds_write_b16_d16_hi v60, v53 offset:62424
	ds_write_b16 v60, v54 offset:63264
	ds_write_b16_d16_hi v60, v54 offset:64104
	ds_write_b16 v60, v55 offset:64944
	ds_write_b16_d16_hi v61, v55 offset:5880
; #define LAS __attribute__((address_space(3)))
; __device__ __forceinline__ unsigned pk2(float lo, float hi) { return pg8::cvt_pk_bf16(lo, hi); }
; __device__ __forceinline__ void attn_phase(LAS unsigned char* lds, const bf16* qkv, bf16* o, const float* qg, const float* kg, const float* sink, int G, int c) {
;     ...
;         for (int i = 0; i < 7; ++i) {
;             const int part = tid & 7, o = tid >> 3;
;             int slot = -1;
;             if (i < 6) { const int Bc = (meta ? 0 : j - 1) + (i >> 1); if (Bc >= Blo && Bc <= Bhi && (first || Bc == j + 1) && !(meta && i >= 2)) slot = (Bc % 3) * 128 + 64 * (i & 1) + o; }
;             else if (first && o < 32) slot = 384 + o;
;             const v4u kw = kr[i], vw = vr[i];
;             float kf[8] = {bflo(kw.x), bfhi(kw.x), bflo(kw.y), bfhi(kw.y), bflo(kw.z), bfhi(kw.z), bflo(kw.w), bfhi(kw.w)};
;             float ss = 0.f;
; #pragma unroll
;             for (int e = 0; e < 8; ++e) ss += kf[e] * kf[e];
;             ss += __shfl_xor(ss, 1); ss += __shfl_xor(ss, 2); ss += __shfl_xor(ss, 4);
;             const float rs = __builtin_amdgcn_rsqf(ss * (1.0f / 64.0f) + pg8::RMS_EPS);
;             const f32x4 g0 = *(const f32x4*)(kg + part * 8), g1 = *(const f32x4*)(kg + part * 8 + 4);
;             v4u kp; kp.x = pk2(kf[0] * rs * g0.x, kf[1] * rs * g0.y); kp.y = pk2(kf[2] * rs * g0.z, kf[3] * rs * g0.w);
;             kp.z = pk2(kf[4] * rs * g1.x, kf[5] * rs * g1.y); kp.w = pk2(kf[6] * rs * g1.z, kf[7] * rs * g1.w);
;             if (slot >= 0) {
;                 *(LAS v4u*)(lds + K_OFF + slot * KSTR + part * 16) = kp;
;                 LAS unsigned char* vb = lds + V_OFF + (part * 8) * VSTR + slot * 2;
;                 *(LAS unsigned short*)(vb + 0 * VSTR) = (unsigned short)(vw.x & 0xffffu); *(LAS unsigned short*)(vb + 1 * VSTR) = (unsigned short)(vw.x >> 16);
;                 *(LAS unsigned short*)(vb + 2 * VSTR) = (unsigned short)(vw.y & 0xffffu); *(LAS unsigned short*)(vb + 3 * VSTR) = (unsigned short)(vw.y >> 16);
;                 *(LAS unsigned short*)(vb + 4 * VSTR) = (unsigned short)(vw.z & 0xffffu); *(LAS unsigned short*)(vb + 5 * VSTR) = (unsigned short)(vw.z >> 16);
;                 *(LAS unsigned short*)(vb + 6 * VSTR) = (unsigned short)(vw.w & 0xffffu); *(LAS unsigned short*)(vb + 7 * VSTR) = (unsigned short)(vw.w >> 16);
;             }
.LBB0_592:
	s_or_b64 exec, exec, s[40:41]
	s_xor_b64 s[10:11], s[10:11], -1
	v_mov_b32_e32 v61, -1
	v_mul_lo_u16_e32 v60, 0xab, v94
	s_and_saveexec_b64 s[40:41], s[10:11]
	v_lshrrev_b16_e32 v52, 9, v60
	v_mul_lo_u16_e32 v52, 3, v52
	v_sub_u16_e32 v52, v94, v52
	v_and_b32_e32 v52, 0xff, v52
	v_lshl_add_u32 v61, v52, 7, v183
	s_or_b64 exec, exec, s[40:41]
	v_and_b32_e32 v63, 0xffff0000, v56
	v_lshlrev_b32_e32 v62, 16, v56
	v_mul_f32_e32 v52, v63, v63
	v_lshlrev_b32_e32 v64, 16, v57
	v_fmac_f32_e32 v52, v62, v62
	v_and_b32_e32 v65, 0xffff0000, v57
	v_fmac_f32_e32 v52, v64, v64
	v_lshlrev_b32_e32 v66, 16, v58
	v_fmac_f32_e32 v52, v65, v65
	v_and_b32_e32 v67, 0xffff0000, v58
	v_fmac_f32_e32 v52, v66, v66
	v_lshlrev_b32_e32 v68, 16, v59
	v_fmac_f32_e32 v52, v67, v67
	v_and_b32_e32 v69, 0xffff0000, v59
	v_fmac_f32_e32 v52, v68, v68
	v_fmac_f32_e32 v52, v69, v69
	s_nop 1
	v_add_f32_dpp v52, v52, v52 quad_perm:[1,0,3,2] row_mask:0xf bank_mask:0xf
	v_cmp_lt_i32_e32 vcc, -1, v61
	s_nop 1
	v_add_f32_dpp v52, v52, v52 quad_perm:[2,3,0,1] row_mask:0xf bank_mask:0xf
	s_nop 1
	v_add_f32_dpp v52, v52, v52 row_half_mirror row_mask:0xf bank_mask:0xf
	v_fmamk_f32 v52, v52, 0x3c800000, v193
	v_rsq_f32_e32 v70, v52
	global_load_dwordx4 v[52:55], v[158:159], off offset:16
	global_load_dwordx4 v[56:59], v[158:159], off
	v_mul_f32_e32 v62, v70, v62
	s_waitcnt vmcnt(0)
	v_mul_f32_e32 v56, v56, v62
	v_mul_f32_e32 v62, v70, v63
	v_mul_f32_e32 v57, v57, v62
	v_cvt_pk_bf16_f32 v56, v56, v57
	v_mul_f32_e32 v57, v70, v64
	v_mul_f32_e32 v57, v58, v57
	v_mul_f32_e32 v58, v70, v65
	v_mul_f32_e32 v58, v59, v58
	v_cvt_pk_bf16_f32 v57, v57, v58
	v_mul_f32_e32 v58, v70, v66
	v_mul_f32_e32 v52, v52, v58
	v_mul_f32_e32 v58, v70, v67
	v_mul_f32_e32 v53, v53, v58
	v_cvt_pk_bf16_f32 v58, v52, v53
	v_mul_f32_e32 v52, v70, v68
	v_mul_f32_e32 v53, v70, v69
	v_mul_f32_e32 v52, v54, v52
	v_mul_f32_e32 v53, v55, v53
	v_cvt_pk_bf16_f32 v59, v52, v53
	s_and_saveexec_b64 s[40:41], vcc
	s_cbranch_execz .LBB0_596
	s_movk_i32 s4, 0x90
	v_mad_u64_u32 v[52:53], s[6:7], v61, s4, v[154:155]
	ds_write_b128 v52, v[56:59]
	v_lshl_add_u32 v52, v61, 1, v214
	v_add_u32_e32 v53, 0xea00, v52
	ds_write_b16 v52, v48 offset:59904
	ds_write_b16_d16_hi v52, v48 offset:60744
	ds_write_b16 v52, v49 offset:61584
	ds_write_b16_d16_hi v52, v49 offset:62424
	ds_write_b16 v52, v50 offset:63264
	ds_write_b16_d16_hi v52, v50 offset:64104
	ds_write_b16 v52, v51 offset:64944
	ds_write_b16_d16_hi v53, v51 offset:5880
; #define LAS __attribute__((address_space(3)))
; __device__ __forceinline__ unsigned pk2(float lo, float hi) { return pg8::cvt_pk_bf16(lo, hi); }
; __device__ __forceinline__ void attn_phase(LAS unsigned char* lds, const bf16* qkv, bf16* o, const float* qg, const float* kg, const float* sink, int G, int c) {
;     ...
;         for (int i = 0; i < 7; ++i) {
;             const int part = tid & 7, o = tid >> 3;
;             int slot = -1;
;             if (i < 6) { const int Bc = (meta ? 0 : j - 1) + (i >> 1); if (Bc >= Blo && Bc <= Bhi && (first || Bc == j + 1) && !(meta && i >= 2)) slot = (Bc % 3) * 128 + 64 * (i & 1) + o; }
;             else if (first && o < 32) slot = 384 + o;
;             const v4u kw = kr[i], vw = vr[i];
;             float kf[8] = {bflo(kw.x), bfhi(kw.x), bflo(kw.y), bfhi(kw.y), bflo(kw.z), bfhi(kw.z), bflo(kw.w), bfhi(kw.w)};
;             float ss = 0.f;
; #pragma unroll
;             for (int e = 0; e < 8; ++e) ss += kf[e] * kf[e];
;             ss += __shfl_xor(ss, 1); ss += __shfl_xor(ss, 2); ss += __shfl_xor(ss, 4);
;             const float rs = __builtin_amdgcn_rsqf(ss * (1.0f / 64.0f) + pg8::RMS_EPS);
;             const f32x4 g0 = *(const f32x4*)(kg + part * 8), g1 = *(const f32x4*)(kg + part * 8 + 4);
;             v4u kp; kp.x = pk2(kf[0] * rs * g0.x, kf[1] * rs * g0.y); kp.y = pk2(kf[2] * rs * g0.z, kf[3] * rs * g0.w);
;             kp.z = pk2(kf[4] * rs * g1.x, kf[5] * rs * g1.y); kp.w = pk2(kf[6] * rs * g1.z, kf[7] * rs * g1.w);
;             if (slot >= 0) {
;                 *(LAS v4u*)(lds + K_OFF + slot * KSTR + part * 16) = kp;
;                 LAS unsigned char* vb = lds + V_OFF + (part * 8) * VSTR + slot * 2;
;                 *(LAS unsigned short*)(vb + 0 * VSTR) = (unsigned short)(vw.x & 0xffffu); *(LAS unsigned short*)(vb + 1 * VSTR) = (unsigned short)(vw.x >> 16);
;                 *(LAS unsigned short*)(vb + 2 * VSTR) = (unsigned short)(vw.y & 0xffffu); *(LAS unsigned short*)(vb + 3 * VSTR) = (unsigned short)(vw.y >> 16);
;                 *(LAS unsigned short*)(vb + 4 * VSTR) = (unsigned short)(vw.z & 0xffffu); *(LAS unsigned short*)(vb + 5 * VSTR) = (unsigned short)(vw.z >> 16);
;                 *(LAS unsigned short*)(vb + 6 * VSTR) = (unsigned short)(vw.w & 0xffffu); *(LAS unsigned short*)(vb + 7 * VSTR) = (unsigned short)(vw.w >> 16);
;             }
.LBB0_596:
	s_or_b64 exec, exec, s[40:41]
	v_mov_b32_e32 v52, -1
	s_and_saveexec_b64 s[40:41], s[10:11]
	v_lshrrev_b16_e32 v48, 9, v60
	v_mul_lo_u16_e32 v48, 3, v48
	v_sub_u16_e32 v48, v94, v48
	v_and_b32_e32 v48, 0xff, v48
	v_lshl_add_u32 v52, v48, 7, v213
	s_or_b64 exec, exec, s[40:41]
	v_and_b32_e32 v54, 0xffff0000, v44
	v_lshlrev_b32_e32 v53, 16, v44
	v_mul_f32_e32 v44, v54, v54
	v_lshlrev_b32_e32 v55, 16, v45
	v_fmac_f32_e32 v44, v53, v53
	v_and_b32_e32 v56, 0xffff0000, v45
	v_fmac_f32_e32 v44, v55, v55
	v_lshlrev_b32_e32 v57, 16, v46
	v_fmac_f32_e32 v44, v56, v56
	v_and_b32_e32 v58, 0xffff0000, v46
	v_fmac_f32_e32 v44, v57, v57
	v_lshlrev_b32_e32 v59, 16, v47
	v_fmac_f32_e32 v44, v58, v58
	v_and_b32_e32 v60, 0xffff0000, v47
	v_fmac_f32_e32 v44, v59, v59
	v_fmac_f32_e32 v44, v60, v60
	s_nop 1
	v_add_f32_dpp v44, v44, v44 quad_perm:[1,0,3,2] row_mask:0xf bank_mask:0xf
	v_cmp_lt_i32_e32 vcc, -1, v52
	s_nop 1
	v_add_f32_dpp v44, v44, v44 quad_perm:[2,3,0,1] row_mask:0xf bank_mask:0xf
	s_nop 1
	v_add_f32_dpp v44, v44, v44 row_half_mirror row_mask:0xf bank_mask:0xf
	v_fmamk_f32 v44, v44, 0x3c800000, v193
	v_rsq_f32_e32 v61, v44
	global_load_dwordx4 v[44:47], v[158:159], off offset:16
	global_load_dwordx4 v[48:51], v[158:159], off
	v_mul_f32_e32 v53, v61, v53
	s_waitcnt vmcnt(0)
	v_mul_f32_e32 v48, v48, v53
	v_mul_f32_e32 v53, v61, v54
	v_mul_f32_e32 v49, v49, v53
	v_cvt_pk_bf16_f32 v48, v48, v49
	v_mul_f32_e32 v49, v61, v55
	v_mul_f32_e32 v49, v50, v49
	v_mul_f32_e32 v50, v61, v56
	v_mul_f32_e32 v50, v51, v50
	v_cvt_pk_bf16_f32 v49, v49, v50
	v_mul_f32_e32 v50, v61, v57
	v_mul_f32_e32 v44, v44, v50
	v_mul_f32_e32 v50, v61, v58
	v_mul_f32_e32 v45, v45, v50
	v_cvt_pk_bf16_f32 v50, v44, v45
	v_mul_f32_e32 v44, v61, v59
	v_mul_f32_e32 v45, v61, v60
	v_mul_f32_e32 v44, v46, v44
	v_mul_f32_e32 v45, v47, v45
	v_cvt_pk_bf16_f32 v51, v44, v45
	s_and_saveexec_b64 s[10:11], vcc
	s_cbranch_execz .LBB0_600
	s_movk_i32 s4, 0x90
	v_mad_u64_u32 v[44:45], s[6:7], v52, s4, v[154:155]
	ds_write_b128 v44, v[48:51]
	v_lshl_add_u32 v44, v52, 1, v214
	v_add_u32_e32 v45, 0xea00, v44
	ds_write_b16 v44, v24 offset:59904
	ds_write_b16_d16_hi v44, v24 offset:60744
	ds_write_b16 v44, v25 offset:61584
	ds_write_b16_d16_hi v44, v25 offset:62424
	ds_write_b16 v44, v26 offset:63264
	ds_write_b16_d16_hi v44, v26 offset:64104
	ds_write_b16 v44, v27 offset:64944
	ds_write_b16_d16_hi v45, v27 offset:5880
.LBB0_600:
	s_or_b64 exec, exec, s[10:11]
	global_load_dwordx4 v[24:27], v[158:159], off
	global_load_dwordx4 v[44:47], v[158:159], off offset:16
	v_and_b32_e32 v49, 0xffff0000, v40
	v_lshlrev_b32_e32 v48, 16, v40
	v_mul_f32_e32 v40, v49, v49
	v_lshlrev_b32_e32 v50, 16, v41
	v_fmac_f32_e32 v40, v48, v48
	v_and_b32_e32 v41, 0xffff0000, v41
	v_fmac_f32_e32 v40, v50, v50
	v_lshlrev_b32_e32 v51, 16, v42
	v_fmac_f32_e32 v40, v41, v41
	v_and_b32_e32 v42, 0xffff0000, v42
	v_fmac_f32_e32 v40, v51, v51
	v_lshlrev_b32_e32 v52, 16, v43
	v_fmac_f32_e32 v40, v42, v42
	v_and_b32_e32 v43, 0xffff0000, v43
	v_fmac_f32_e32 v40, v52, v52
	v_fmac_f32_e32 v40, v43, v43
	s_nop 1
	v_add_f32_dpp v40, v40, v40 quad_perm:[1,0,3,2] row_mask:0xf bank_mask:0xf
	s_and_b64 vcc, s[74:75], s[96:97]
	s_nop 1
	v_add_f32_dpp v40, v40, v40 quad_perm:[2,3,0,1] row_mask:0xf bank_mask:0xf
	s_nop 1
	v_add_f32_dpp v40, v40, v40 row_half_mirror row_mask:0xf bank_mask:0xf
	v_fmamk_f32 v40, v40, 0x3c800000, v193
	v_rsq_f32_e32 v53, v40
	v_add_u32_e32 v40, 0x180, v183
	v_cndmask_b32_e32 v40, -1, v40, vcc
	v_cmp_lt_i32_e32 vcc, -1, v40
	v_mul_f32_e32 v48, v53, v48
	v_mul_f32_e32 v49, v53, v49
	v_mul_f32_e32 v50, v53, v50
	v_mul_f32_e32 v41, v53, v41
	v_mul_f32_e32 v51, v53, v51
	v_mul_f32_e32 v42, v53, v42
	v_mul_f32_e32 v52, v53, v52
	v_mul_f32_e32 v43, v53, v43
	s_waitcnt vmcnt(1)
	v_mul_f32_e32 v24, v24, v48
	v_mul_f32_e32 v25, v25, v49
	v_mul_f32_e32 v26, v26, v50
	v_mul_f32_e32 v27, v27, v41
	s_waitcnt vmcnt(0)
	v_mul_f32_e32 v41, v44, v51
	v_mul_f32_e32 v42, v45, v42
	v_mul_f32_e32 v44, v46, v52
	v_mul_f32_e32 v43, v47, v43
	v_cvt_pk_bf16_f32 v24, v24, v25
	v_cvt_pk_bf16_f32 v25, v26, v27
	v_cvt_pk_bf16_f32 v26, v41, v42
	v_cvt_pk_bf16_f32 v27, v44, v43
	s_and_saveexec_b64 s[10:11], vcc
	s_cbranch_execz .LBB0_602
	s_movk_i32 s4, 0x90
	v_mad_u64_u32 v[42:43], s[6:7], v40, s4, v[154:155]
	ds_write_b128 v42, v[24:27]
	v_lshl_add_u32 v24, v40, 1, v214
	v_add_u32_e32 v25, 0xea00, v24
	ds_write_b16 v24, v16 offset:59904
	ds_write_b16_d16_hi v24, v16 offset:60744
	ds_write_b16 v24, v17 offset:61584
	ds_write_b16_d16_hi v24, v17 offset:62424
	ds_write_b16 v24, v18 offset:63264
	ds_write_b16_d16_hi v24, v18 offset:64104
	ds_write_b16 v24, v19 offset:64944
	ds_write_b16_d16_hi v25, v19 offset:5880
